# v86 + static s_setprio 1 for waves 4-7 during the rebuilt GEMM phases (w_in, w_o, gate/up, down), reset to 0 at the next phase
# speedup vs baseline: 1.0032x; 1.0032x over previous
.LBB0_224:
	v_readfirstlane_b32 s99, v0
	s_cmp_lt_u32 s99, 0x100
	s_cbranch_scc1 .Lprio_skip2
	s_setprio 1

.LBB0_361:
	s_setprio 0
	s_cmp_gt_i32 s18, 3
	s_cselect_b64 s[20:21], -1, 0
	s_cmp_lt_i32 s19, 4
	s_cselect_b64 s[2:3], -1, 0
	s_or_b64 s[2:3], s[20:21], s[2:3]
	s_and_b64 vcc, exec, s[2:3]
	s_cbranch_vccnz .LBB0_436
	s_andn2_b64 vcc, exec, s[6:7]
	s_cbranch_vccnz .LBB0_364
	s_cbranch_execz .LBB0_365
	s_branch .LBB0_418

.LBB0_1020:
	s_setprio 0
	s_cmp_gt_i32 s18, 7
	s_cselect_b64 s[12:13], -1, 0
	s_cmp_lt_i32 s19, 8
	s_cselect_b64 s[2:3], -1, 0
	s_or_b64 s[2:3], s[12:13], s[2:3]
	s_and_b64 vcc, exec, s[2:3]
	s_cbranch_vccnz .LBB0_1081
	s_andn2_b64 vcc, exec, s[8:9]
	s_cbranch_vccnz .LBB0_1023
	s_cbranch_execz .LBB0_1024
	s_branch .LBB0_1077

.LBB0_1241:
	s_setprio 0
	v_readfirstlane_b32 s99, v0
	s_cmp_lt_u32 s99, 0x100
	s_cbranch_scc1 .Lprio_skip9
	s_setprio 1

.LBB0_1362:
	s_setprio 0
	s_cmp_gt_i32 s18, 10
	s_cselect_b64 s[12:13], -1, 0
	s_cmp_lt_i32 s19, 11
	s_cselect_b64 s[2:3], -1, 0
	s_or_b64 s[2:3], s[12:13], s[2:3]
	s_and_b64 vcc, exec, s[2:3]
	s_cbranch_vccnz .LBB0_1467
	s_andn2_b64 vcc, exec, s[8:9]
	s_cbranch_vccnz .LBB0_1365
	s_cbranch_execz .LBB0_1366
	s_branch .LBB0_1419

.LBB0_1604:
	s_setprio 0
	s_cmp_gt_i32 s18, 12
	s_cselect_b64 s[20:21], -1, 0
	s_cmp_lt_i32 s19, 13
	s_cselect_b64 s[2:3], -1, 0
	s_or_b64 s[2:3], s[20:21], s[2:3]
	s_and_b64 vcc, exec, s[2:3]
	s_cbranch_vccnz .LBB0_1679
	s_andn2_b64 vcc, exec, s[6:7]
	s_cbranch_vccnz .LBB0_1607
	s_cbranch_execz .LBB0_1608
	s_branch .LBB0_1661

.LBB0_2263:
	s_setprio 0
	s_cmp_gt_i32 s18, 16
	s_cselect_b64 s[12:13], -1, 0
	s_cmp_lt_i32 s19, 17
	s_cselect_b64 s[2:3], -1, 0
	s_or_b64 s[2:3], s[12:13], s[2:3]
	s_and_b64 vcc, exec, s[2:3]
	s_cbranch_vccnz .LBB0_2324
	s_andn2_b64 vcc, exec, s[8:9]
	s_cbranch_vccnz .LBB0_2266
	s_cbranch_execz .LBB0_2267
	s_branch .LBB0_2320
